# P6 residual epilogue: x loads marked nt (read-once stream), stores default
# speedup vs baseline: 1.0870x; 1.0043x over previous
.LBB0_566:
	v_lshl_add_u32 v152, s28, 8, v142
	v_lshl_or_b32 v154, s54, 8, v144
	v_ashrrev_i32_e32 v153, 31, v152
	v_ashrrev_i32_e32 v155, 31, v154
	v_lshlrev_b64 v[140:141], 11, v[152:153]
	v_lshl_add_u64 v[140:141], v[140:141], 0, v[154:155]
	v_lshlrev_b64 v[140:141], 2, v[140:141]
	s_andn2_b64 vcc, exec, s[0:1]
	s_mov_b64 s[0:1], -1
	v_mov_b32_e32 v224, v140
	v_or_b32_e32 v225, 16, v152
	v_lshl_add_u32 v225, v225, 11, v154
	v_lshlrev_b32_e32 v225, 2, v225
	v_or_b32_e32 v226, 32, v152
	v_lshl_add_u32 v226, v226, 11, v154
	v_lshlrev_b32_e32 v226, 2, v226
	v_or_b32_e32 v227, 48, v152
	v_lshl_add_u32 v227, v227, 11, v154
	v_lshlrev_b32_e32 v227, 2, v227
	v_add_u32_e32 v228, s10, v140
	v_add_u32_e32 v229, s12, v140
	v_add_u32_e32 v230, s14, v140
	v_add_u32_e32 v231, s18, v140
	global_load_dwordx4 v[160:163], v224, s[16:17] nt
	global_load_dwordx4 v[164:167], v224, s[16:17] offset:64 nt
	global_load_dwordx4 v[168:171], v224, s[16:17] offset:512 nt
	global_load_dwordx4 v[172:175], v224, s[16:17] offset:576 nt
	global_load_dwordx4 v[176:179], v225, s[16:17] nt
	global_load_dwordx4 v[180:183], v225, s[16:17] offset:64 nt
	global_load_dwordx4 v[184:187], v225, s[16:17] offset:512 nt
	global_load_dwordx4 v[188:191], v225, s[16:17] offset:576 nt
	global_load_dwordx4 v[192:195], v226, s[16:17] nt
	global_load_dwordx4 v[196:199], v226, s[16:17] offset:64 nt
	global_load_dwordx4 v[200:203], v226, s[16:17] offset:512 nt
	global_load_dwordx4 v[204:207], v226, s[16:17] offset:576 nt
	global_load_dwordx4 v[208:211], v227, s[16:17] nt
	global_load_dwordx4 v[212:215], v227, s[16:17] offset:64 nt
	global_load_dwordx4 v[216:219], v227, s[16:17] offset:512 nt
	global_load_dwordx4 v[220:223], v227, s[16:17] offset:576 nt
	s_waitcnt vmcnt(15)
	v_pk_add_f32 v[124:125], v[124:125], v[160:161]
	v_pk_add_f32 v[126:127], v[126:127], v[162:163]
	global_store_dwordx4 v224, v[124:127], s[50:51]
	global_load_dwordx4 v[160:163], v228, s[16:17] nt
	s_waitcnt vmcnt(16)
	v_pk_add_f32 v[120:121], v[120:121], v[164:165]
	v_pk_add_f32 v[122:123], v[122:123], v[166:167]
	global_store_dwordx4 v224, v[120:123], s[50:51] offset:64
	global_load_dwordx4 v[164:167], v228, s[16:17] offset:64 nt
	s_waitcnt vmcnt(17)
	v_pk_add_f32 v[116:117], v[116:117], v[168:169]
	v_pk_add_f32 v[118:119], v[118:119], v[170:171]
	global_store_dwordx4 v224, v[116:119], s[50:51] offset:512
	global_load_dwordx4 v[168:171], v228, s[16:17] offset:512 nt
	s_waitcnt vmcnt(18)
	v_pk_add_f32 v[104:105], v[104:105], v[172:173]
	v_pk_add_f32 v[106:107], v[106:107], v[174:175]
	global_store_dwordx4 v224, v[104:107], s[50:51] offset:576
	global_load_dwordx4 v[172:175], v228, s[16:17] offset:576 nt
	s_waitcnt vmcnt(19)
	v_pk_add_f32 v[112:113], v[112:113], v[176:177]
	v_pk_add_f32 v[114:115], v[114:115], v[178:179]
	global_store_dwordx4 v225, v[112:115], s[50:51]
	global_load_dwordx4 v[176:179], v229, s[16:17] nt
	s_waitcnt vmcnt(20)
	v_pk_add_f32 v[108:109], v[108:109], v[180:181]
	v_pk_add_f32 v[110:111], v[110:111], v[182:183]
	global_store_dwordx4 v225, v[108:111], s[50:51] offset:64
	global_load_dwordx4 v[180:183], v229, s[16:17] offset:64 nt
	s_waitcnt vmcnt(21)
	v_pk_add_f32 v[100:101], v[100:101], v[184:185]
	v_pk_add_f32 v[102:103], v[102:103], v[186:187]
	global_store_dwordx4 v225, v[100:103], s[50:51] offset:512
	global_load_dwordx4 v[184:187], v229, s[16:17] offset:512 nt
	s_waitcnt vmcnt(22)
	v_pk_add_f32 v[88:89], v[88:89], v[188:189]
	v_pk_add_f32 v[90:91], v[90:91], v[190:191]
	global_store_dwordx4 v225, v[88:91], s[50:51] offset:576
	global_load_dwordx4 v[188:191], v229, s[16:17] offset:576 nt
	s_waitcnt vmcnt(23)
	v_pk_add_f32 v[96:97], v[96:97], v[192:193]
	v_pk_add_f32 v[98:99], v[98:99], v[194:195]
	global_store_dwordx4 v226, v[96:99], s[50:51]
	global_load_dwordx4 v[192:195], v230, s[16:17] nt
	s_waitcnt vmcnt(24)
	v_pk_add_f32 v[92:93], v[92:93], v[196:197]
	v_pk_add_f32 v[94:95], v[94:95], v[198:199]
	global_store_dwordx4 v226, v[92:95], s[50:51] offset:64
	global_load_dwordx4 v[196:199], v230, s[16:17] offset:64 nt
	s_waitcnt vmcnt(25)
	v_pk_add_f32 v[84:85], v[84:85], v[200:201]
	v_pk_add_f32 v[86:87], v[86:87], v[202:203]
	global_store_dwordx4 v226, v[84:87], s[50:51] offset:512
	global_load_dwordx4 v[200:203], v230, s[16:17] offset:512 nt
	s_waitcnt vmcnt(26)
	v_pk_add_f32 v[72:73], v[72:73], v[204:205]
	v_pk_add_f32 v[74:75], v[74:75], v[206:207]
	global_store_dwordx4 v226, v[72:75], s[50:51] offset:576
	global_load_dwordx4 v[204:207], v230, s[16:17] offset:576 nt
	s_waitcnt vmcnt(27)
	v_pk_add_f32 v[80:81], v[80:81], v[208:209]
	v_pk_add_f32 v[82:83], v[82:83], v[210:211]
	global_store_dwordx4 v227, v[80:83], s[50:51]
	global_load_dwordx4 v[208:211], v231, s[16:17] nt
	s_waitcnt vmcnt(28)
	v_pk_add_f32 v[76:77], v[76:77], v[212:213]
	v_pk_add_f32 v[78:79], v[78:79], v[214:215]
	global_store_dwordx4 v227, v[76:79], s[50:51] offset:64
	global_load_dwordx4 v[212:215], v231, s[16:17] offset:64 nt
	s_waitcnt vmcnt(29)
	v_pk_add_f32 v[68:69], v[68:69], v[216:217]
	v_pk_add_f32 v[70:71], v[70:71], v[218:219]
	global_store_dwordx4 v227, v[68:71], s[50:51] offset:512
	global_load_dwordx4 v[216:219], v231, s[16:17] offset:512 nt
	s_waitcnt vmcnt(30)
	v_pk_add_f32 v[64:65], v[64:65], v[220:221]
	v_pk_add_f32 v[66:67], v[66:67], v[222:223]
	global_store_dwordx4 v227, v[64:67], s[50:51] offset:576
	global_load_dwordx4 v[220:223], v231, s[16:17] offset:576 nt
	s_waitcnt vmcnt(30)
	v_pk_add_f32 v[60:61], v[60:61], v[160:161]
	v_pk_add_f32 v[62:63], v[62:63], v[162:163]
	global_store_dwordx4 v228, v[60:63], s[50:51]
	s_waitcnt vmcnt(29)
	v_pk_add_f32 v[56:57], v[56:57], v[164:165]
	v_pk_add_f32 v[58:59], v[58:59], v[166:167]
	global_store_dwordx4 v228, v[56:59], s[50:51] offset:64
	s_waitcnt vmcnt(28)
	v_pk_add_f32 v[52:53], v[52:53], v[168:169]
	v_pk_add_f32 v[54:55], v[54:55], v[170:171]
	global_store_dwordx4 v228, v[52:55], s[50:51] offset:512
	s_waitcnt vmcnt(27)
	v_pk_add_f32 v[40:41], v[40:41], v[172:173]
	v_pk_add_f32 v[42:43], v[42:43], v[174:175]
	global_store_dwordx4 v228, v[40:43], s[50:51] offset:576
	s_waitcnt vmcnt(26)
	v_pk_add_f32 v[48:49], v[48:49], v[176:177]
	v_pk_add_f32 v[50:51], v[50:51], v[178:179]
	global_store_dwordx4 v229, v[48:51], s[50:51]
	s_waitcnt vmcnt(25)
	v_pk_add_f32 v[44:45], v[44:45], v[180:181]
	v_pk_add_f32 v[46:47], v[46:47], v[182:183]
	global_store_dwordx4 v229, v[44:47], s[50:51] offset:64
	s_waitcnt vmcnt(24)
	v_pk_add_f32 v[36:37], v[36:37], v[184:185]
	v_pk_add_f32 v[38:39], v[38:39], v[186:187]
	global_store_dwordx4 v229, v[36:39], s[50:51] offset:512
	s_waitcnt vmcnt(23)
	v_pk_add_f32 v[24:25], v[24:25], v[188:189]
	v_pk_add_f32 v[26:27], v[26:27], v[190:191]
	global_store_dwordx4 v229, v[24:27], s[50:51] offset:576
	s_waitcnt vmcnt(22)
	v_pk_add_f32 v[32:33], v[32:33], v[192:193]
	v_pk_add_f32 v[34:35], v[34:35], v[194:195]
	global_store_dwordx4 v230, v[32:35], s[50:51]
	s_waitcnt vmcnt(21)
	v_pk_add_f32 v[28:29], v[28:29], v[196:197]
	v_pk_add_f32 v[30:31], v[30:31], v[198:199]
	global_store_dwordx4 v230, v[28:31], s[50:51] offset:64
	s_waitcnt vmcnt(20)
	v_pk_add_f32 v[20:21], v[20:21], v[200:201]
	v_pk_add_f32 v[22:23], v[22:23], v[202:203]
	global_store_dwordx4 v230, v[20:23], s[50:51] offset:512
	s_waitcnt vmcnt(19)
	v_pk_add_f32 v[8:9], v[8:9], v[204:205]
	v_pk_add_f32 v[10:11], v[10:11], v[206:207]
	global_store_dwordx4 v230, v[8:11], s[50:51] offset:576
	s_waitcnt vmcnt(18)
	v_pk_add_f32 v[16:17], v[16:17], v[208:209]
	v_pk_add_f32 v[18:19], v[18:19], v[210:211]
	global_store_dwordx4 v231, v[16:19], s[50:51]
	s_waitcnt vmcnt(17)
	v_pk_add_f32 v[12:13], v[12:13], v[212:213]
	v_pk_add_f32 v[14:15], v[14:15], v[214:215]
	global_store_dwordx4 v231, v[12:15], s[50:51] offset:64
	s_waitcnt vmcnt(16)
	v_pk_add_f32 v[4:5], v[4:5], v[216:217]
	v_pk_add_f32 v[6:7], v[6:7], v[218:219]
	global_store_dwordx4 v231, v[4:7], s[50:51] offset:512
	s_waitcnt vmcnt(15)
	v_pk_add_f32 v[0:1], v[0:1], v[220:221]
	v_pk_add_f32 v[2:3], v[2:3], v[222:223]
	global_store_dwordx4 v231, v[0:3], s[50:51] offset:576
	s_cbranch_vccnz .LBB0_555
	s_andn2_b64 vcc, exec, s[4:5]
	s_cbranch_vccnz .LBB0_554
	s_barrier
	s_branch .LBB0_554
